# P2 pooling units after the first dealt from a device counter with one unit of look-ahead instead of the static stride
# baseline (speedup 1.0000x reference)
.LBB0_508:
	s_and_b64 vcc, exec, s[0:1]
	s_cbranch_vccz .LBB0_510
	v_readlane_b32 s0, v253, 18
	v_readlane_b32 s1, v253, 19
	s_andn2_b64 vcc, exec, s[0:1]
	s_mov_b32 s20, s2
	s_cbranch_vccnz .LBB0_510
	s_cmp_lg_u32 s3, 0x100
	s_cbranch_scc1 .LBB0_558
	v_cmp_eq_u32_e64 s[100:101], 0, v204
	s_and_saveexec_b64 s[98:99], s[100:101]
	s_cbranch_execz .Lpd_ia
	v_readlane_b32 s100, v253, 36
	v_readlane_b32 s101, v253, 37
	s_add_u32 s100, s100, 0x1c
	s_addc_u32 s101, s101, 0
	v_mov_b32_e32 v223, 1
	global_atomic_add v223, v1, v223, s[100:101] sc0
.Lpd_ia:
	s_or_b64 exec, exec, s[98:99]
	s_branch .LBB0_558

.Lpd_next:
	v_cmp_eq_u32_e32 vcc, 0, v204
	s_and_saveexec_b64 s[98:99], vcc
	s_cbranch_execz .Lpd_n1
	s_waitcnt vmcnt(0)
	v_add_u32_e32 v2, 0x100, v223
	v_mov_b32_e32 v0, s10
	ds_write_b32 v0, v2
.Lpd_n1:
	s_or_b64 exec, exec, s[98:99]
	v_mov_b32_e32 v0, s10
	s_waitcnt lgkmcnt(0)
	s_barrier
	ds_read_b32 v0, v0
	s_waitcnt lgkmcnt(0)
	v_readfirstlane_b32 s20, v0
	s_cmpk_gt_i32 s20, 0x21f
	s_cbranch_scc1 .LBB0_510
	v_cmp_eq_u32_e64 s[100:101], 0, v204
	s_and_saveexec_b64 s[98:99], s[100:101]
	s_cbranch_execz .Lpd_ib
	v_readlane_b32 s100, v253, 36
	v_readlane_b32 s101, v253, 37
	s_add_u32 s100, s100, 0x1c
	s_addc_u32 s101, s101, 0
	v_mov_b32_e32 v223, 1
	global_atomic_add v223, v1, v223, s[100:101] sc0
.Lpd_ib:
	s_or_b64 exec, exec, s[98:99]
.LBB0_558:
	s_mul_hi_i32 s0, s20, 0x87878787
	s_lshr_b32 s1, s0, 31
	s_ashr_i32 s0, s0, 6
	s_add_i32 s0, s0, s1
	s_add_i32 s36, s0, 3
	s_mul_hi_i32 s0, s20, 0x78787879
	s_lshr_b32 s1, s0, 31
	s_ashr_i32 s0, s0, 6
	s_add_i32 s0, s0, s1
	s_mulk_i32 s0, 0x88
	s_sub_i32 s21, s20, s0
	s_cmpk_gt_i32 s21, 0x7f
	s_mov_b64 s[0:1], -1
	s_cbranch_scc0 .LBB0_623
	s_add_i32 s0, s21, 0xffffff80
	s_lshl_b32 s22, s0, 5
	s_mul_hi_u32 s1, s0, 0x7800
	s_mulk_i32 s0, 0x7800
	v_readlane_b32 s12, v253, 21
	v_readlane_b32 s13, v253, 22
	s_add_u32 s19, s12, s0
	s_addc_u32 s23, s13, s1
	s_lshl_b32 s72, s36, 7
	v_mov_b32_e32 v161, v204
	s_lshl_b64 s[0:1], s[72:73], 2
	s_add_u32 s0, s19, s0
	v_and_b32_e32 v176, 15, v161
	s_addc_u32 s1, s23, s1
	v_lshlrev_b32_e32 v0, 5, v176
	s_waitcnt lgkmcnt(0)
	v_lshl_add_u64 v[2:3], s[0:1], 0, v[0:1]
	s_add_i32 s19, s22, 0x3ff1
	s_lshl_b32 s0, s36, 8
	s_add_u32 s0, s68, s0
	s_addc_u32 s1, s69, 0
	v_lshlrev_b32_e32 v0, 4, v176
	v_lshl_add_u64 v[4:5], s[0:1], 0, v[0:1]
	s_movk_i32 s0, 0x2f0
	v_ashrrev_i32_e32 v150, 4, v161
	v_cmp_gt_i32_e64 s[0:1], s0, v161
	v_mov_b32_e32 v130, 0
	v_mov_b32_e32 v134, 0
	v_mov_b32_e32 v135, 0
	v_mov_b32_e32 v136, 0
	v_mov_b32_e32 v137, 0
	s_and_saveexec_b64 s[38:39], s[0:1]
	s_cbranch_execz .LBB0_566
	v_cmp_gt_i32_e32 vcc, 15, v150
	s_and_saveexec_b64 s[24:25], vcc
	s_xor_b64 s[42:43], exec, s[24:25]
	s_cbranch_execz .LBB0_563
	v_readlane_b32 s12, v253, 23
	v_readlane_b32 s13, v253, 24
	s_andn2_b64 vcc, exec, s[12:13]
	s_cbranch_vccnz .LBB0_660
	v_ashrrev_i32_e32 v151, 31, v150
	v_lshlrev_b64 v[6:7], 11, v[150:151]
	v_lshl_add_u64 v[10:11], v[2:3], 0, v[6:7]
	global_load_dwordx4 v[6:9], v[10:11], off
	s_nop 0
	global_load_dwordx4 v[10:13], v[10:11], off offset:16
	s_waitcnt vmcnt(0)
	v_cvt_pk_bf16_f32 v134, v6, v7
	v_cvt_pk_bf16_f32 v135, v8, v9
	v_cvt_pk_bf16_f32 v136, v10, v11
	v_cvt_pk_bf16_f32 v137, v12, v13
